# lru_local conv-halo: 3 serialized ushort loads issued together; in-proj copy-out: 4 LDS reads in flight per iteration with counted lgkmcnt
# speedup vs baseline: 1.0096x; 1.0017x over previous
; template <int EPI>
; __device__ void gemm_phase256(const Params& P, int l, const bf16_t* __restrict__ A, const bf16_t* __restrict__ Bt, int NT, char* smem) {
;     ...
; #pragma unroll 4
;       for (int k = 0; k < 16; ++k) {
;         const int c = tid + 256 * k;
;         const int row = c >> 4, c8 = (c & 15) * 8;
;         if (c8 < nvalid) {
;           const uint4 v = *(const uint4*)(Cs + row * 136 + c8);
;           *(uint4*)(dstb + (size_t)(m0 + row) * dstride + cbase + c8) = v;
;         }
;       }
.LBB0_265:
	s_and_saveexec_b64 s[38:39], vcc
	s_cbranch_execz .LBB0_264
	v_add_u32_e32 v136, s1, v179
	v_ashrrev_i32_e32 v134, 4, v136
	v_mad_u64_u32 v[130:131], s[40:41], v134, s67, v[190:191]
	ds_read_b128 v[140:143], v130
	v_add_u32_e32 v134, s7, v134
	s_movk_i32 s37, 0x1030
	v_mad_i64_i32 v[156:157], s[40:41], v134, s37, v[128:129]
	v_add_u32_e32 v130, 0x100, v136
	v_ashrrev_i32_e32 v134, 4, v130
	v_mad_u64_u32 v[130:131], s[40:41], v134, s67, v[190:191]
	ds_read_b128 v[144:147], v130
	v_add_u32_e32 v134, s7, v134
	v_mad_i64_i32 v[158:159], s[40:41], v134, s37, v[128:129]
	v_add_u32_e32 v130, 0x200, v136
	v_ashrrev_i32_e32 v134, 4, v130
	v_mad_u64_u32 v[130:131], s[40:41], v134, s67, v[190:191]
	ds_read_b128 v[148:151], v130
	v_add_u32_e32 v134, s7, v134
	v_mad_i64_i32 v[160:161], s[40:41], v134, s37, v[128:129]
	v_add_u32_e32 v130, 0x300, v136
	v_ashrrev_i32_e32 v134, 4, v130
	v_mad_u64_u32 v[130:131], s[40:41], v134, s67, v[190:191]
	ds_read_b128 v[152:155], v130
	v_add_u32_e32 v134, s7, v134
	v_mad_i64_i32 v[134:135], s[40:41], v134, s37, v[128:129]
	s_waitcnt lgkmcnt(3)
	global_store_dwordx4 v[156:157], v[140:143], off
	s_waitcnt lgkmcnt(2)
	global_store_dwordx4 v[158:159], v[144:147], off
	s_waitcnt lgkmcnt(1)
	global_store_dwordx4 v[160:161], v[148:151], off
	s_waitcnt lgkmcnt(0)
	global_store_dwordx4 v[134:135], v[152:155], off
	s_branch .LBB0_264

; DEV float bf2f(unsigned short h) { return __uint_as_float(((unsigned)h) << 16); }
; __device__ void lru_local_item(const Params& P, int l, int item, char* smem) {
;     ...
;   bf16x8 bw[2][4][2];
;   {
;     const bf16_t* wt = P.WgT + (size_t)(l * 8 + n) * 2 * 4096;
; #pragma unroll
;     for (int mat = 0; mat < 2; ++mat)
; #pragma unroll
;       for (int nt = 0; nt < 4; ++nt)
; #pragma unroll
;         for (int ks = 0; ks < 2; ++ks) bw[mat][nt][ks] = *(const bf16x8*)(wt + mat * 4096 + (nt * 16 + r16) * 64 + ks * 32 + kq * 8);
;   }
;   const float cw0 = P.conv_w[l * 4 * 512 + 0 * 512 + ch], cw1 = P.conv_w[l * 4 * 512 + 1 * 512 + ch];
;   const float cw2 = P.conv_w[l * 4 * 512 + 2 * 512 + ch], cw3 = P.conv_w[l * 4 * 512 + 3 * 512 + ch];
;   const float cb = P.conv_b[l * 512 + ch], ba = P.lru_ba[l * 512 + ch], bx = P.lru_bx[l * 512 + ch];
;   const float lam = P.lru_lambda[l * 512 + ch];
;   const float z = -lam;
;   const float sp = fmaxf(z, 0.f) + log1pf(__expf(-fabsf(z)));
;   const float nl = -8.0f * sp;
;   const int s0 = j * 64;
;   const bf16_t* hx = P.H + (size_t)(b * SEQ) * HS + ch;
;   float xm3 = (s0 - 3 >= 0) ? bf2f(hx[(size_t)(s0 - 3) * HS]) : 0.f;
;   float xm2 = (s0 - 2 >= 0) ? bf2f(hx[(size_t)(s0 - 2) * HS]) : 0.f;
;   float xm1 = (s0 - 1 >= 0) ? bf2f(hx[(size_t)(s0 - 1) * HS]) : 0.f;
.LBB0_287:
	s_cmpk_gt_i32 s37, 0x1ff
	s_mov_b64 s[0:1], -1
	s_cbranch_scc0 .LBB0_299
	s_add_i32 s0, s37, 0xfffffe00
	s_lshl_b32 s1, s0, 8
	v_mov_b32_e32 v68, v202
	s_and_b32 s1, s1, 0x100
	v_readlane_b32 s44, v251, 42
	v_add_u32_e32 v64, s1, v68
	v_ashrrev_i32_e32 v0, 6, v64
	v_add_u32_e32 v0, v0, v226
	v_ashrrev_i32_e32 v1, 31, v0
	v_lshlrev_b64 v[0:1], 14, v[0:1]
	v_readlane_b32 s45, v251, 43
	v_and_b32_e32 v176, 48, v68
	v_and_b32_e32 v69, 15, v68
	v_lshl_add_u64 v[0:1], s[44:45], 0, v[0:1]
	v_readlane_b32 s46, v251, 44
	v_readlane_b32 s47, v251, 45
	v_readlane_b32 s48, v251, 46
	v_readlane_b32 s49, v251, 47
	v_readlane_b32 s50, v251, 48
	v_readlane_b32 s51, v251, 49
	v_readlane_b32 s52, v251, 50
	v_readlane_b32 s53, v251, 51
	v_readlane_b32 s54, v251, 52
	v_readlane_b32 s55, v251, 53
	v_readlane_b32 s56, v251, 54
	v_readlane_b32 s57, v251, 55
	v_readlane_b32 s58, v251, 56
	v_readlane_b32 s59, v251, 57
	v_lshl_add_u64 v[32:33], v[0:1], 0, v[176:177]
	s_mov_b64 s[38:39], 0x2000
	s_lshr_b32 s41, s0, 7
	v_readlane_b32 s0, v248, 28
	v_lshlrev_b32_e32 v40, 7, v69
	v_mov_b32_e32 v41, v177
	v_lshl_add_u64 v[58:59], v[32:33], 0, s[38:39]
	v_add_u32_e32 v66, s0, v64
	v_readlane_b32 s44, v251, 10
	v_lshl_add_u64 v[12:13], v[32:33], 0, v[40:41]
	v_or_b32_e32 v48, 0x1000, v40
	v_mov_b32_e32 v49, v177
	v_or_b32_e32 v56, 0x1800, v40
	v_mov_b32_e32 v57, v177
	v_lshl_add_u64 v[36:37], v[58:59], 0, v[40:41]
	v_or_b32_e32 v40, 0x800, v40
	v_ashrrev_i32_e32 v67, 31, v66
	v_readlane_b32 s50, v251, 16
	v_readlane_b32 s51, v251, 17
	v_lshl_add_u64 v[20:21], v[32:33], 0, v[48:49]
	v_lshl_add_u64 v[28:29], v[32:33], 0, v[56:57]
	v_lshl_add_u64 v[44:45], v[58:59], 0, v[40:41]
	v_lshl_add_u64 v[52:53], v[58:59], 0, v[48:49]
	v_lshl_add_u64 v[60:61], v[58:59], 0, v[56:57]
	v_lshl_add_u64 v[70:71], v[66:67], 2, s[50:51]
	v_readlane_b32 s0, v248, 15
	global_load_dwordx4 v[0:3], v[12:13], off
	global_load_dwordx4 v[4:7], v[12:13], off offset:64
	global_load_dwordx4 v[8:11], v[12:13], off offset:2048
	s_nop 0
	global_load_dwordx4 v[12:15], v[12:13], off offset:2112
	s_nop 0
	global_load_dwordx4 v[16:19], v[20:21], off
	s_nop 0
	global_load_dwordx4 v[20:23], v[20:21], off offset:64
	s_nop 0
	global_load_dwordx4 v[24:27], v[28:29], off
	s_nop 0
	global_load_dwordx4 v[28:31], v[28:29], off offset:64
	s_nop 0
	global_load_dwordx4 v[32:35], v[36:37], off
	s_nop 0
	global_load_dwordx4 v[36:39], v[36:37], off offset:64
	s_nop 0
	global_load_dwordx4 v[40:43], v[44:45], off
	s_nop 0
	global_load_dwordx4 v[44:47], v[44:45], off offset:64
	s_nop 0
	global_load_dwordx4 v[48:51], v[52:53], off
	s_nop 0
	global_load_dwordx4 v[52:55], v[52:53], off offset:64
	s_nop 0
	global_load_dwordx4 v[56:59], v[60:61], off
	s_nop 0
	global_load_dwordx4 v[60:63], v[60:61], off offset:64
	s_nop 0
	global_load_dword v80, v[70:71], off
	global_load_dword v81, v[70:71], off offset:2048
	v_add_u32_e32 v70, s0, v64
	v_ashrrev_i32_e32 v71, 31, v70
	v_lshl_add_u64 v[70:71], v[70:71], 2, s[50:51]
	v_readlane_b32 s0, v248, 16
	global_load_dword v82, v[70:71], off
	v_readlane_b32 s52, v251, 18
	v_add_u32_e32 v70, s0, v64
	v_readlane_b32 s0, v248, 20
	v_ashrrev_i32_e32 v71, 31, v70
	v_readlane_b32 s53, v251, 19
	v_add_u32_e32 v66, s0, v66
	v_ashrrev_i32_e32 v67, 31, v66
	v_lshl_add_u64 v[70:71], v[70:71], 2, s[50:51]
	v_lshlrev_b64 v[66:67], 2, v[66:67]
	v_readlane_b32 s45, v251, 11
	v_readlane_b32 s46, v251, 12
	v_readlane_b32 s47, v251, 13
	v_readlane_b32 s48, v251, 14
	v_readlane_b32 s49, v251, 15
	v_readlane_b32 s54, v251, 20
	v_readlane_b32 s55, v251, 21
	v_readlane_b32 s56, v251, 22
	v_readlane_b32 s57, v251, 23
	v_readlane_b32 s58, v251, 24
	v_readlane_b32 s59, v251, 25
	global_load_dword v83, v[70:71], off
	v_lshl_add_u64 v[70:71], s[52:53], 0, v[66:67]
	global_load_dword v84, v[70:71], off
	v_lshl_add_u64 v[70:71], s[56:57], 0, v[66:67]
	v_readlane_b32 s44, v251, 26
	v_readlane_b32 s45, v251, 27
	v_readlane_b32 s46, v251, 28
	v_readlane_b32 s47, v251, 29
	global_load_dword v85, v[70:71], off
	v_lshl_add_u64 v[70:71], s[44:45], 0, v[66:67]
	v_lshl_add_u64 v[66:67], s[46:47], 0, v[66:67]
	global_load_dword v86, v[70:71], off
	s_bfe_u32 s40, s37, 0x60001
	global_load_dword v70, v[66:67], off
	v_readlane_b32 s1, v248, 29
	s_mul_i32 s2, s41, 0x818000
	s_lshl_b32 s42, s40, 6
	s_lshl_b64 s[0:1], s[2:3], 1
	s_add_u32 s0, s26, s0
	s_addc_u32 s1, s27, s1
	v_ashrrev_i32_e32 v65, 31, v64
	s_cmp_lg_u32 s40, 0
	v_lshl_add_u64 v[66:67], v[64:65], 1, s[0:1]
	v_mov_b32_e32 v87, 0
	s_cselect_b64 s[38:39], -1, 0
	s_cmp_eq_u32 s40, 0
	v_mov_b32_e32 v88, 0
	v_readlane_b32 s48, v251, 30
	v_readlane_b32 s49, v251, 31
	v_readlane_b32 s50, v251, 32
	v_readlane_b32 s51, v251, 33
	v_readlane_b32 s52, v251, 34
	v_readlane_b32 s53, v251, 35
	v_readlane_b32 s54, v251, 36
	v_readlane_b32 s55, v251, 37
	v_readlane_b32 s56, v251, 38
	v_readlane_b32 s57, v251, 39
	v_readlane_b32 s58, v251, 40
	v_readlane_b32 s59, v251, 41
	s_cbranch_scc1 .LBB0_290
	s_add_i32 s0, s42, -3
	v_mad_u64_u32 v[72:73], s[0:1], s0, v221, v[66:67]
	global_load_ushort v88, v[72:73], off
.LBB0_290:
	v_cndmask_b32_e64 v71, 0, 1, s[38:39]
	v_cmp_ne_u32_e64 s[0:1], 1, v71
	s_andn2_b64 vcc, exec, s[38:39]
	s_mov_b64 s[46:47], 0x1000
	s_cbranch_vccnz .LBB0_292
	s_add_i32 s2, s42, -2
	v_mad_u64_u32 v[72:73], s[38:39], s2, v221, v[66:67]
	global_load_ushort v87, v[72:73], off
.LBB0_292:
	v_mov_b32_e32 v72, 0
	s_and_b64 vcc, exec, s[0:1]
	v_mov_b32_e32 v89, 0
	s_cbranch_vccnz .LBB0_294
	s_add_i32 s0, s42, -1
	v_mad_u64_u32 v[74:75], s[0:1], s0, v221, v[66:67]
	global_load_ushort v89, v[74:75], off
; DEV float bf2f(unsigned short h) { return __uint_as_float(((unsigned)h) << 16); }
; __device__ void lru_local_item(const Params& P, int l, int item, char* smem) {
;     ...
;   const float lam = P.lru_lambda[l * 512 + ch];
;   const float z = -lam;
;   const float sp = fmaxf(z, 0.f) + log1pf(__expf(-fabsf(z)));
;   const float nl = -8.0f * sp;
;   const int s0 = j * 64;
;   const bf16_t* hx = P.H + (size_t)(b * SEQ) * HS + ch;
;   float xm3 = (s0 - 3 >= 0) ? bf2f(hx[(size_t)(s0 - 3) * HS]) : 0.f;
;   float xm2 = (s0 - 2 >= 0) ? bf2f(hx[(size_t)(s0 - 2) * HS]) : 0.f;
;   float xm1 = (s0 - 1 >= 0) ? bf2f(hx[(size_t)(s0 - 1) * HS]) : 0.f;
;   float h = 0.f, pc = 1.f;
;   unsigned short hv[16], hn[16];
; #pragma unroll
;   for (int i = 0; i < 16; ++i) { hv[i] = hx[(size_t)(s0 + i) * HS]; hn[i] = hv[i]; }
.LBB0_294:
	s_mov_b32 s0, 0xbfb8aa3b
	s_waitcnt vmcnt(0)
	v_lshlrev_b32_e32 v88, 16, v88
	v_lshlrev_b32_e32 v87, 16, v87
	v_lshlrev_b32_e32 v89, 16, v89
	v_mul_f32_e64 v71, |v70|, s0
	v_exp_f32_e32 v114, v71
	v_max_f32_e64 v70, -v70, -v70
	v_max_f32_e32 v115, 0, v70
	s_mov_b32 s0, 0x3f2aaaab
	v_add_f32_e32 v74, 1.0, v114
	v_add_f32_e32 v70, -1.0, v74
	v_sub_f32_e32 v71, v70, v74
	v_add_f32_e32 v71, 1.0, v71
	v_sub_f32_e32 v70, v114, v70
	v_add_f32_e32 v75, v70, v71
	v_frexp_mant_f32_e32 v76, v74
	v_cvt_f64_f32_e32 v[70:71], v74
	v_frexp_exp_i32_f64_e32 v70, v[70:71]
	v_cmp_gt_f32_e32 vcc, s0, v76
	s_mul_i32 s0, s40, 0x40c00
	s_mov_b32 s1, s3
	v_subbrev_co_u32_e32 v116, vcc, 0, v70, vcc
	v_sub_u32_e32 v70, 0, v116
	v_ldexp_f32 v71, v74, v70
	v_add_f32_e32 v74, -1.0, v71
	v_add_f32_e32 v77, 1.0, v71
	v_ldexp_f32 v70, v75, v70
	v_add_f32_e32 v75, 1.0, v74
	v_add_f32_e32 v90, -1.0, v77
	v_sub_f32_e32 v75, v71, v75
	v_sub_f32_e32 v71, v71, v90
	v_add_f32_e32 v75, v70, v75
	v_add_f32_e32 v70, v70, v71
	v_add_f32_e32 v71, v77, v70
	v_rcp_f32_e32 v90, v71
	v_add_f32_e32 v76, v74, v75
	v_sub_f32_e32 v74, v76, v74
	v_sub_f32_e32 v74, v75, v74
	v_sub_f32_e32 v75, v71, v77
	v_sub_f32_e32 v70, v70, v75
	v_mul_f32_e32 v75, v76, v90
	v_mul_f32_e32 v77, v71, v75
	v_fma_f32 v91, v75, v71, -v77
	v_fmac_f32_e32 v91, v75, v70
	v_add_f32_e32 v92, v77, v91
	v_sub_f32_e32 v93, v76, v92
	v_sub_f32_e32 v76, v76, v93
	v_sub_f32_e32 v77, v92, v77
	v_sub_f32_e32 v76, v76, v92
	v_add_f32_e32 v74, v74, v76
	v_sub_f32_e32 v76, v77, v91
	v_add_f32_e32 v74, v76, v74
	v_add_f32_e32 v76, v93, v74
	v_mul_f32_e32 v77, v90, v76
	v_mul_f32_e32 v91, v71, v77
	v_fma_f32 v71, v77, v71, -v91
	v_fmac_f32_e32 v71, v77, v70
	v_sub_f32_e32 v70, v93, v76
	v_add_f32_e32 v70, v74, v70
	v_add_f32_e32 v74, v91, v71
	v_sub_f32_e32 v92, v76, v74
	v_sub_f32_e32 v76, v76, v92
	v_sub_f32_e32 v91, v74, v91
	v_sub_f32_e32 v74, v76, v74
	v_add_f32_e32 v70, v70, v74
	v_sub_f32_e32 v71, v91, v71
	v_add_f32_e32 v70, v71, v70
	v_add_f32_e32 v117, v75, v77
	v_add_f32_e32 v70, v92, v70
	v_sub_f32_e32 v71, v117, v75
	v_mul_f32_e32 v70, v90, v70
	v_sub_f32_e32 v71, v77, v71
	v_add_f32_e32 v118, v71, v70
	v_lshl_add_u64 v[70:71], v[66:67], 0, s[0:1]
	s_movk_i32 s0, 0x1000
	v_add_co_u32_e32 v74, vcc, s0, v70
	s_movk_i32 s0, 0x3000
	s_nop 0
	v_addc_co_u32_e32 v75, vcc, 0, v71, vcc
	v_add_co_u32_e32 v76, vcc, s65, v70
	v_add_f32_e32 v119, v117, v118
	s_nop 0
	v_addc_co_u32_e32 v77, vcc, 0, v71, vcc
	v_add_co_u32_e32 v90, vcc, s0, v70
	s_movk_i32 s0, 0x5000
	s_nop 0
	v_addc_co_u32_e32 v91, vcc, 0, v71, vcc
	v_add_co_u32_e32 v92, vcc, s97, v70
	s_lshl_b32 s1, s37, 14
	s_nop 0
	v_addc_co_u32_e32 v93, vcc, 0, v71, vcc
	v_add_co_u32_e32 v94, vcc, s0, v70
	s_movk_i32 s0, 0x6000
	s_nop 0
	v_addc_co_u32_e32 v95, vcc, 0, v71, vcc
	v_add_co_u32_e32 v104, vcc, s0, v70
	s_movk_i32 s0, 0x7000
	s_nop 0
	v_addc_co_u32_e32 v105, vcc, 0, v71, vcc
	v_add_co_u32_e32 v106, vcc, s0, v70
	s_mov_b32 s0, 0x8000
	s_nop 0
	v_addc_co_u32_e32 v107, vcc, 0, v71, vcc
	global_load_ushort v103, v[70:71], off
	global_load_ushort v101, v[74:75], off offset:48
	global_load_ushort v100, v[76:77], off offset:96
	global_load_ushort v99, v[90:91], off offset:144
	global_load_ushort v98, v[92:93], off offset:192
	global_load_ushort v97, v[94:95], off offset:240
	global_load_ushort v96, v[104:105], off offset:288
	global_load_ushort v102, v[106:107], off offset:336
	v_add_co_u32_e32 v74, vcc, s0, v70
	s_mov_b32 s0, 0x9000
	s_nop 0
	v_addc_co_u32_e32 v75, vcc, 0, v71, vcc
	v_add_co_u32_e32 v76, vcc, s0, v70
	s_mov_b32 s0, 0xa000
	s_nop 0
	v_addc_co_u32_e32 v77, vcc, 0, v71, vcc
	v_add_co_u32_e32 v90, vcc, s0, v70
; DEV float bf2f(unsigned short h) { return __uint_as_float(((unsigned)h) << 16); }
; __device__ void lru_local_item(const Params& P, int l, int item, char* smem) {
;     ...
;   const float sp = fmaxf(z, 0.f) + log1pf(__expf(-fabsf(z)));
;   const float nl = -8.0f * sp;
;   const int s0 = j * 64;
;   const bf16_t* hx = P.H + (size_t)(b * SEQ) * HS + ch;
;   float xm3 = (s0 - 3 >= 0) ? bf2f(hx[(size_t)(s0 - 3) * HS]) : 0.f;
;   float xm2 = (s0 - 2 >= 0) ? bf2f(hx[(size_t)(s0 - 2) * HS]) : 0.f;
;   float xm1 = (s0 - 1 >= 0) ? bf2f(hx[(size_t)(s0 - 1) * HS]) : 0.f;
;   float h = 0.f, pc = 1.f;
;   unsigned short hv[16], hn[16];
; #pragma unroll
;   for (int i = 0; i < 16; ++i) { hv[i] = hx[(size_t)(s0 + i) * HS]; hn[i] = hv[i]; }
	s_mov_b32 s0, 0xb000
	s_nop 0
	v_addc_co_u32_e32 v91, vcc, 0, v71, vcc
	v_add_co_u32_e32 v92, vcc, s0, v70
	s_mov_b32 s0, 0xc000
	s_nop 0
	v_addc_co_u32_e32 v93, vcc, 0, v71, vcc
	v_add_co_u32_e32 v94, vcc, s0, v70
	s_mov_b32 s0, 0xd000
	s_nop 0
	v_addc_co_u32_e32 v95, vcc, 0, v71, vcc
	v_add_co_u32_e32 v104, vcc, s0, v70
	s_mov_b32 s0, 0xe000
	s_nop 0
	v_addc_co_u32_e32 v105, vcc, 0, v71, vcc
	v_add_co_u32_e32 v112, vcc, s0, v70
	s_mov_b32 s0, 0xf000
	s_nop 0
	v_addc_co_u32_e32 v113, vcc, 0, v71, vcc
	v_add_co_u32_e32 v70, vcc, s0, v70
	s_mov_b32 s0, 0x3f317218
	s_nop 0
	v_addc_co_u32_e32 v71, vcc, 0, v71, vcc
	global_load_ushort v111, v[74:75], off offset:384
	global_load_ushort v109, v[76:77], off offset:432
	global_load_ushort v108, v[90:91], off offset:480
	global_load_ushort v107, v[92:93], off offset:528
	global_load_ushort v106, v[94:95], off offset:576
	s_nop 0
	global_load_ushort v105, v[104:105], off offset:624
	s_nop 0
	global_load_ushort v104, v[112:113], off offset:672
	global_load_ushort v110, v[70:71], off offset:720
	v_cvt_f32_i32_e32 v70, v116
	v_mul_f32_e32 v71, v119, v119
	v_fmamk_f32 v74, v71, 0x3e9b6dac, v205
	v_fmaak_f32 v74, v71, v74, 0x3f2aaada
	v_mul_f32_e32 v75, 0x3f317218, v70
	v_fma_f32 v76, v70, s0, -v75
	v_fmac_f32_e32 v76, 0xb102e308, v70
	v_add_f32_e32 v77, v75, v76
	v_sub_f32_e32 v75, v77, v75
	v_mul_f32_e32 v71, v119, v71
	v_sub_f32_e32 v75, v76, v75
	v_ldexp_f32 v76, v119, 1
	v_mul_f32_e32 v71, v71, v74
	v_sub_f32_e32 v70, v119, v117
	v_add_f32_e32 v74, v76, v71
	v_sub_f32_e32 v70, v118, v70
	v_sub_f32_e32 v76, v74, v76
	v_ldexp_f32 v70, v70, 1
	v_sub_f32_e32 v71, v71, v76
	v_add_f32_e32 v70, v70, v71
	v_add_f32_e32 v71, v74, v70
	v_sub_f32_e32 v74, v71, v74
	v_sub_f32_e32 v70, v70, v74
	v_add_f32_e32 v74, v77, v71
	v_sub_f32_e32 v76, v74, v77
	v_sub_f32_e32 v90, v74, v76
	v_sub_f32_e32 v77, v77, v90
	v_sub_f32_e32 v71, v71, v76
	v_add_f32_e32 v76, v75, v70
	v_add_f32_e32 v71, v71, v77
	v_sub_f32_e32 v77, v76, v75
	v_sub_f32_e32 v90, v76, v77
	v_sub_f32_e32 v75, v75, v90
	v_sub_f32_e32 v70, v70, v77
	v_add_f32_e32 v71, v76, v71
	v_add_f32_e32 v70, v70, v75
	v_add_f32_e32 v75, v74, v71
	v_sub_f32_e32 v74, v75, v74
	v_sub_f32_e32 v71, v71, v74
	v_add_f32_e32 v70, v70, v71
	s_mov_b32 s0, 0x7f800000
	v_add_f32_e32 v70, v75, v70
	v_cmp_neq_f32_e32 vcc, s0, v114
	s_mov_b32 s0, 0x33800000
	s_and_b32 s1, s1, 0x1f8000
	v_cndmask_b32_e32 v70, v222, v70, vcc
	v_cmp_ngt_f32_e32 vcc, -1.0, v114
	v_bfe_u32 v79, v68, 4, 2
	v_lshlrev_b32_e32 v71, 7, v68
	v_cndmask_b32_e32 v70, v223, v70, vcc
	v_cmp_neq_f32_e32 vcc, -1.0, v114
	v_and_b32_e32 v73, 63, v68
	v_and_b32_e32 v71, 0xffffe000, v71
	v_cndmask_b32_e32 v70, v224, v70, vcc
	v_cmp_lt_f32_e64 vcc, |v114|, s0
	s_lshl_b32 s0, s33, 14
	s_and_b32 s0, s0, 0xffe00000
	v_cndmask_b32_e32 v70, v70, v114, vcc
	v_add_f32_e32 v70, v115, v70
	v_mul_f32_e32 v90, 0xc1000000, v70
	v_lshlrev_b32_e32 v70, 1, v68
	v_sub_u32_e32 v74, 0, v70
	v_and_b32_e32 v70, 0x7fffffc0, v68
	s_or_b32 s2, s0, s1
	v_lshlrev_b32_e32 v70, 1, v70
	s_movk_i32 s1, 0x210
	s_and_b32 s0, s7, 0x100
	v_mad_u32_u24 v75, v69, s1, v70
	v_lshlrev_b32_e32 v70, 10, v79
	v_lshlrev_b32_e32 v69, 2, v69
	v_lshlrev_b32_e32 v91, 2, v68
	v_or3_b32 v92, v71, v70, v69
	v_lshl_or_b32 v69, v73, 2, v71
	v_add_u32_e32 v68, s0, v68
	v_add_u32_e32 v93, 0x6200, v69
	v_ashrrev_i32_e32 v69, 31, v68
	v_lshl_add_u64 v[68:69], v[68:69], 0, s[2:3]
	v_lshlrev_b64 v[70:71], 1, v[68:69]
	v_mov_b32_e32 v78, 1.0
	s_mov_b32 s38, 0
	v_lshl_add_u64 v[68:69], s[60:61], 0, v[70:71]
	v_lshl_add_u64 v[70:71], s[62:63], 0, v[70:71]
	v_add_u32_e32 v94, v91, v74
	v_add_u32_e32 v95, v75, v176
	s_mov_b32 s39, s2
	s_waitcnt vmcnt(0)
